# moba pairing: one item step moved from the two classes that reach barrier 5 last (15,2)->(15,1), (13,4)->(12,4) to the scan class, which gained slack from the pipelined scan: (0,12)->(0,13), (1,11)->(
# speedup vs baseline: 1.0002x; 1.0002x over previous
.LBB0_565:
	s_cbranch_execz .LBB0_643
	s_lshl_b32 s0, s76, 2
	s_and_b32 s73, s0, 28
	s_lshl_b32 s0, s76, 11
	s_ashr_i32 s33, s76, 3
	s_lshr_b32 s98, s33, 3
	s_lshl_b32 s98, s98, 2
	s_lshr_b32 s98, 0xacef8920, s98
	s_and_b32 s98, s98, 15
	s_sub_i32 s98, 15, s98
	s_lshl_b32 s98, s98, 3
	s_and_b32 s33, s33, 7
	s_or_b32 s33, s33, s98
	s_and_b32 s52, s0, 0x3000
	s_ashr_i32 s2, s42, 3
	s_not_b32 s72, s33
	s_or_b32 s74, s52, 64
	s_add_u32 s66, s58, 0x2cd1000
	s_addc_u32 s67, s59, 0
	s_add_u32 s75, s58, 0x8cd1000
	s_addc_u32 s77, s59, 0
	s_add_u32 s78, s58, 0xbd0000
	v_mbcnt_lo_u32_b32 v0, -1, 0
	s_addc_u32 s79, s59, 0
	v_mbcnt_hi_u32_b32 v196, -1, v0
	s_mov_b32 s63, 0
	s_add_u32 s68, s58, 0xcd1000
	v_and_b32_e32 v0, 64, v196
	s_mov_b32 s53, s63
	s_addc_u32 s69, s59, 0
	v_mov_b32_e32 v33, 0
	s_movk_i32 s80, 0xff
	s_movk_i32 s81, 0x1800
	s_mov_b32 s82, 0xefa18f08
	v_xor_b32_e32 v197, 32, v196
	v_add_u32_e32 v198, 64, v0
	v_mov_b32_e32 v199, 0xff800000
	v_mov_b32_e32 v200, 0x3f803f80
	s_mov_b32 s6, 0
	s_mov_b32 s83, 0
	v_readlane_b32 s98, v255, 14
	s_nop 3
	s_cmp_lg_u32 s98, 0
	s_cbranch_scc1 .Lmoba_dq_latch2
	s_branch .LBB0_569

.Lmoba_dq_latch2:
	s_waitcnt lgkmcnt(0)
	s_barrier
	v_readlane_b32 s98, v255, 19
	s_nop 3
	s_cmp_lg_u32 s98, 0
	s_cbranch_scc1 .LBB0_643
	s_mov_b32 s98, 1
	s_nop 0
	v_writelane_b32 v255, s98, 19
	s_ashr_i32 s14, s76, 3
	s_lshr_b32 s0, s14, 3
	s_lshl_b32 s0, s0, 2
	s_lshr_b32 s0, 0x743165bd, s0
	s_and_b32 s0, s0, 15
	s_sub_i32 s0, 15, s0
	s_lshl_b32 s0, s0, 3
	s_and_b32 s14, s14, 7
	s_or_b32 s14, s14, s0
	s_branch .LBB0_574
